# adds: HGRN2 prompt scan waits only for the operand pieces it stages (counted vmcnt), keeping the set requested one chunk ago in flight
# speedup vs baseline: 1.0016x; 1.0009x over previous
.LBB0_808:
	v_cmp_lt_i32_e32 vcc, s27, v94
	s_cmp_eq_u32 s67, 60
	s_cbranch_scc1 .Lhg_tail
	s_waitcnt vmcnt(3)
	ds_write_b128 v102, v[40:43] offset:31232
	s_waitcnt vmcnt(2)
	s_branch .Lhg_w2
.Lhg_tail:
	s_waitcnt vmcnt(0)
	ds_write_b128 v102, v[40:43] offset:31232
.Lhg_w2:
	ds_write_b128 v103, v[44:47] offset:39936
	s_and_saveexec_b64 s[34:35], vcc
	s_xor_b64 s[34:35], exec, s[34:35]
	s_cbranch_execnz .LBB0_811
	s_andn2_saveexec_b64 s[34:35], s[34:35]
	s_cbranch_execnz .LBB0_818

.LBB0_841:
	v_cmp_lt_i32_e32 vcc, s27, v106
	s_waitcnt vmcnt(3)
	ds_write_b128 v102, v[48:51]
	s_waitcnt vmcnt(2)
	ds_write_b128 v103, v[52:55] offset:8704
	s_and_saveexec_b64 s[34:35], vcc
	s_xor_b64 s[34:35], exec, s[34:35]
	s_cbranch_execnz .LBB0_844
	s_andn2_saveexec_b64 s[34:35], s[34:35]
	s_cbranch_execnz .LBB0_851
